# FFN-up0 idle-round weight prep rebalanced: waves 1024..1535 do the W2 transposes (two each), waves 0..1023 the pool-weight folds
# speedup vs baseline: 1.0069x; 1.0069x over previous
; template <bool GATEMAP = false>
; __device__ __forceinline__ void p0_transpose_item(const float* W, int N, bf16* WT, int ldwt, int koff, const float* gain, LAS float* scr, int item, int lane) {
;     const int nblk = N / 64, kb = item / nblk, nb = item % nblk, k0 = 64 * kb, n0 = 64 * nb; const int nd0 = GATEMAP ? gate_row(n0) : n0;
;     const int ks = lane >> 4, n4 = (lane & 15) * 4;
;     f32x4 v[16];
; #pragma unroll
;     for (int i = 0; i < 16; ++i) v[i] = *(const f32x4*)(W + (size_t)(k0 + 4 * i + ks) * N + n0 + n4);
; template <int PART>
; __device__ __forceinline__ void phase_prologue_late(const Params& p, LAS unsigned char* lds, int cu0) {
;     int tid_ = threadIdx.x; asm volatile("" : "+v"(tid_)); const int tid = tid_, lane = tid & 63, wave = __builtin_amdgcn_readfirstlane(tid >> 6);
;     if ((int)blockIdx.x < cu0) return;
;     const int nb = gridDim.x - cu0, gw = (blockIdx.x - cu0) * 8 + wave, NGW = nb * 8;
;     LAS float* scr = (LAS float*)(lds + wave * 16640);
;     unsigned char* ws = p.ws;
;     constexpr int I_W1 = 16 * 64, I_W2 = 64 * 16, I_IN1 = 16 * 24, I_OUT1 = 8 * 16;
;     if (PART == 1) {
;         for (int it = gw; it < 16 * 16 + I_W1 + I_IN1 + I_OUT1; it += NGW) {
;             int r = it;
;             if (r < 16 * 16) { p0_transpose_item(p.in[13], D, (bf16*)(ws + WS_WOUT0), D, 0, nullptr, scr, r, lane); continue; } r -= 16 * 16;
;             if (r < I_W1) { p0_transpose_item(p.in[22], FF, (bf16*)(ws + WS_W1_0), D, 0, p.in[6], scr, r, lane); continue; } r -= I_W1;
;             if (r < I_IN1) { p0_transpose_item(p.in[14], NZ1, (bf16*)(ws + WS_WIN1), D, 0, p.in[5] + D, scr, r, lane); continue; } r -= I_IN1;
;             p0_transpose_item(p.in[21] + (size_t)512 * D, D, (bf16*)(ws + WS_WOUT1), D, 512, nullptr, scr, r, lane);
;         }
;         return;
;     }
;     if (PART == 3) {
;         for (int it = gw; it < I_W1 + I_W2; it += NGW) {
;             int r = it;
;             if (r < I_W1) { p0_transpose_item(p.in[22] + (size_t)D * FF, FF, (bf16*)(ws + WS_W1_1), D, 0, p.in[6] + D, scr, r, lane); continue; } r -= I_W1;
;             p0_transpose_item(p.in[23] + (size_t)D * FF, D, (bf16*)(ws + WS_W2_1), FF, 0, nullptr, scr, r, lane);
;         }
;         return;
;     }
;     for (int it = gw; it < I_W2; it += NGW) p0_transpose_item(p.in[23], D, (bf16*)(ws + WS_W2_0), FF, 0, nullptr, scr, it, lane);
.LBB0_505:
	s_abs_i32 s0, s10
	v_cvt_f32_u32_e32 v0, s0
	s_sub_i32 s3, 0, s0
	s_add_i32 s1, s10, 0x43f
	s_xor_b32 s2, s1, s10
	v_rcp_iflag_f32_e32 v0, v0
	s_abs_i32 s1, s1
	s_ashr_i32 s2, s2, 31
	v_mov_b32_e32 v40, v238
	v_mul_f32_e32 v0, 0x4f7ffffe, v0
	v_cvt_u32_f32_e32 v0, v0
	s_nop 0
	v_readfirstlane_b32 s4, v0
	s_mul_i32 s3, s3, s4
	s_mul_hi_u32 s3, s4, s3
	s_add_i32 s4, s4, s3
	s_mul_hi_u32 s3, s1, s4
	s_mul_i32 s4, s3, s0
	s_sub_i32 s1, s1, s4
	s_add_i32 s5, s3, 1
	s_sub_i32 s4, s1, s0
	s_cmp_ge_u32 s1, s0
	s_cselect_b32 s3, s5, s3
	s_cselect_b32 s1, s4, s1
	s_add_i32 s4, s3, 1
	s_cmp_ge_u32 s1, s0
	s_cselect_b32 s0, s4, s3
	s_not_b32 s1, s2
	s_xor_b32 s0, s0, s2
	s_add_i32 s0, s1, s0
	s_mul_i32 s0, s0, s10
	s_sub_i32 s0, 0x440, s0
	s_cmp_lt_i32 s0, s10
	s_cselect_b32 s6, s0, 0
	s_cmp_lt_i32 s33, s6
	v_readfirstlane_b32 s0, v40
	s_cbranch_scc1 .LBB0_521
	s_sub_i32 s8, s33, s6
	s_ashr_i32 s0, s0, 6
	s_lshl_b32 s1, s8, 3
	s_sub_i32 s7, s10, s6
	s_add_i32 s9, s1, s0
	s_cmpk_eq_i32 s7, 0xc0
	s_cbranch_scc1 .Lprep2_507
	s_cmpk_gt_i32 s9, 0x3ff
	s_cbranch_scc1 .LBB0_513
.Lprep2_507:
	v_lshlrev_b32_e32 v0, 4, v40
	v_and_b32_e32 v2, 0xf0, v0
	v_lshlrev_b32_e32 v0, 3, v40
	s_mulk_i32 s0, 0x4100
	v_and_b32_e32 v0, 56, v0
	s_add_i32 s0, s0, 0
	v_bfe_u32 v8, v40, 4, 2
	v_bfe_u32 v9, v40, 3, 3
	v_lshlrev_b32_e32 v4, 1, v0
	v_mov_b32_e32 v5, 0
	v_add_u32_e32 v6, s0, v2
	v_mul_u32_u24_e32 v7, 0x104, v8
	v_mul_u32_u24_e32 v3, 0x104, v0
	v_lshl_add_u64 v[0:1], s[40:41], 0, v[4:5]
	v_lshlrev_b32_e32 v4, 2, v9
	v_readlane_b32 s52, v254, 5
	v_add3_u32 v10, s0, v3, v4
	v_mov_b32_e32 v3, v5
	v_readlane_b32 s66, v254, 19
	v_readlane_b32 s67, v254, 20
	v_add_u32_e32 v11, v6, v7
	s_lshl_b32 s12, s7, 3
	v_and_b32_e32 v41, 63, v40
	v_lshl_add_u64 v[2:3], s[66:67], 0, v[2:3]
	s_lshl_b32 s4, s9, 6
	s_lshl_b32 s5, s7, 9
	v_add_u32_e32 v12, 0x410, v11
	v_add_u32_e32 v13, 0x418, v11
	v_add_u32_e32 v14, 0x820, v11
	v_add_u32_e32 v15, 0x828, v11
	v_add_u32_e32 v16, 0xc30, v11
	v_add_u32_e32 v17, 0xc38, v11
	v_add_u32_e32 v18, 0x1040, v11
	v_add_u32_e32 v19, 0x1048, v11
	v_add_u32_e32 v20, 0x1450, v11
	v_add_u32_e32 v21, 0x1458, v11
	v_add_u32_e32 v22, 0x1860, v11
	v_add_u32_e32 v23, 0x1868, v11
	v_add_u32_e32 v24, 0x1c70, v11
	v_add_u32_e32 v25, 0x1c78, v11
	v_add_u32_e32 v26, 0x2080, v11
	v_add_u32_e32 v27, 0x2088, v11
	v_add_u32_e32 v28, 0x2490, v11
	v_add_u32_e32 v29, 0x2498, v11
	v_add_u32_e32 v30, 0x28a0, v11
	v_add_u32_e32 v31, 0x28a8, v11
	v_add_u32_e32 v32, 0x2cb0, v11
	v_add_u32_e32 v33, 0x2cb8, v11
	v_add_u32_e32 v34, 0x30c0, v11
	v_add_u32_e32 v35, 0x30c8, v11
	v_add_u32_e32 v36, 0x34d0, v11
	v_add_u32_e32 v37, 0x34d8, v11
	v_add_u32_e32 v38, 0x38e0, v11
	v_add_u32_e32 v39, 0x38e8, v11
	v_add_u32_e32 v42, 0x3cf0, v11
	v_add_u32_e32 v43, 0x3cf8, v11
	v_add_u32_e32 v44, 0x400, v10
	s_mov_b32 s13, s9
	v_readlane_b32 s53, v254, 6
	v_readlane_b32 s54, v254, 7
	v_readlane_b32 s55, v254, 8
	v_readlane_b32 s56, v254, 9
	v_readlane_b32 s57, v254, 10
	v_readlane_b32 s58, v254, 11
	v_readlane_b32 s59, v254, 12
	v_readlane_b32 s60, v254, 13
	v_readlane_b32 s61, v254, 14
	v_readlane_b32 s62, v254, 15
	v_readlane_b32 s63, v254, 16
	v_readlane_b32 s64, v254, 17
	v_readlane_b32 s65, v254, 18
	s_cmpk_lg_i32 s7, 0xc0
	s_cbranch_scc1 .LBB0_508
	s_cmpk_lt_i32 s9, 0x400
	s_cbranch_scc1 .Lprep2_skipw2
	s_sub_i32 s13, s9, 0x400
	s_lshl_b32 s4, s13, 6
	s_movk_i32 s12, 0x200
	s_mov_b32 s5, 0x8000
.LBB0_508:
	s_ashr_i32 s0, s13, 31
	s_lshr_b32 s0, s0, 28
	s_add_i32 s0, s13, s0
	s_ashr_i32 s0, s0, 4
	s_lshl_b32 s2, s0, 6
	s_lshl_b32 s0, s0, 10
	v_or_b32_e32 v46, s2, v8
	s_sub_i32 s0, s4, s0
	v_or_b32_e32 v48, 4, v46
	v_or_b32_e32 v50, 8, v46
	v_or_b32_e32 v52, 12, v46
	v_or_b32_e32 v54, 16, v46
	v_or_b32_e32 v56, 20, v46
	v_or_b32_e32 v58, 24, v46
	v_or_b32_e32 v60, 28, v46
	v_or_b32_e32 v62, 32, v46
	v_or_b32_e32 v64, 36, v46
	v_or_b32_e32 v66, 40, v46
	v_or_b32_e32 v68, 44, v46
	v_or_b32_e32 v70, 48, v46
	v_or_b32_e32 v72, 52, v46
	v_or_b32_e32 v74, 56, v46
	v_or_b32_e32 v76, 60, v46
	s_ashr_i32 s1, s0, 31
	v_ashrrev_i32_e32 v47, 31, v46
	v_ashrrev_i32_e32 v49, 31, v48
	v_ashrrev_i32_e32 v51, 31, v50
	v_ashrrev_i32_e32 v53, 31, v52
	v_ashrrev_i32_e32 v55, 31, v54
	v_ashrrev_i32_e32 v57, 31, v56
	v_ashrrev_i32_e32 v59, 31, v58
	v_ashrrev_i32_e32 v61, 31, v60
	v_ashrrev_i32_e32 v63, 31, v62
	v_ashrrev_i32_e32 v65, 31, v64
	v_ashrrev_i32_e32 v67, 31, v66
	v_ashrrev_i32_e32 v69, 31, v68
	v_ashrrev_i32_e32 v71, 31, v70
	v_ashrrev_i32_e32 v73, 31, v72
	v_ashrrev_i32_e32 v75, 31, v74
	v_ashrrev_i32_e32 v77, 31, v76
	v_lshl_add_u64 v[78:79], s[0:1], 2, v[2:3]
	v_lshlrev_b64 v[46:47], 12, v[46:47]
	v_lshlrev_b64 v[80:81], 12, v[48:49]
	v_lshlrev_b64 v[50:51], 12, v[50:51]
	v_lshlrev_b64 v[52:53], 12, v[52:53]
	v_lshlrev_b64 v[54:55], 12, v[54:55]
	v_lshlrev_b64 v[56:57], 12, v[56:57]
	v_lshlrev_b64 v[58:59], 12, v[58:59]
	v_lshlrev_b64 v[60:61], 12, v[60:61]
	v_lshlrev_b64 v[62:63], 12, v[62:63]
	v_lshlrev_b64 v[64:65], 12, v[64:65]
	v_lshlrev_b64 v[66:67], 12, v[66:67]
	v_lshlrev_b64 v[68:69], 12, v[68:69]
	v_lshlrev_b64 v[70:71], 12, v[70:71]
	v_lshlrev_b64 v[72:73], 12, v[72:73]
	v_lshlrev_b64 v[74:75], 12, v[74:75]
	v_lshlrev_b64 v[76:77], 12, v[76:77]
	v_lshl_add_u64 v[46:47], v[78:79], 0, v[46:47]
	v_lshl_add_u64 v[80:81], v[78:79], 0, v[80:81]
	v_lshl_add_u64 v[82:83], v[78:79], 0, v[50:51]
	v_lshl_add_u64 v[84:85], v[78:79], 0, v[52:53]
	v_lshl_add_u64 v[86:87], v[78:79], 0, v[54:55]
	v_lshl_add_u64 v[88:89], v[78:79], 0, v[56:57]
	v_lshl_add_u64 v[90:91], v[78:79], 0, v[58:59]
	v_lshl_add_u64 v[92:93], v[78:79], 0, v[60:61]
	v_lshl_add_u64 v[94:95], v[78:79], 0, v[62:63]
; #define LAS __attribute__((address_space(3)))
; __device__ __forceinline__ unsigned pk2(float lo, float hi) { return pg8::cvt_pk_bf16(lo, hi); }
; __host__ __device__ __forceinline__ int gate_row(int n) { if (n < 512) return n; const int base = n < 1536 ? 512 : 1536, q = n - base, h = q >> 9, t = (q & 511) >> 7, r = q & 127; return base + t * 256 + h * 128 + r; }
; template <bool GATEMAP = false>
; __device__ __forceinline__ void p0_transpose_item(const float* W, int N, bf16* WT, int ldwt, int koff, const float* gain, LAS float* scr, int item, int lane) {
;     const int nblk = N / 64, kb = item / nblk, nb = item % nblk, k0 = 64 * kb, n0 = 64 * nb; const int nd0 = GATEMAP ? gate_row(n0) : n0;
;     const int ks = lane >> 4, n4 = (lane & 15) * 4;
;     f32x4 v[16];
; #pragma unroll
;     for (int i = 0; i < 16; ++i) v[i] = *(const f32x4*)(W + (size_t)(k0 + 4 * i + ks) * N + n0 + n4);
;     if (gain) {
; #pragma unroll
;         for (int i = 0; i < 16; ++i) v[i] = v[i] * gain[k0 + 4 * i + ks];
;     }
; #pragma unroll
;     for (int i = 0; i < 16; ++i) { LAS float* d = scr + (4 * i + ks) * 65 + n4; d[0] = v[i][0]; d[1] = v[i][1]; d[2] = v[i][2]; d[3] = v[i][3]; }
;     asm volatile("s_waitcnt lgkmcnt(0)" ::: "memory");
;     const int c = lane & 7;
; #pragma unroll
;     for (int j = 0; j < 8; ++j) { const int n = (lane >> 3) + 8 * j; const LAS float* q = scr + (8 * c) * 65 + n;
;         v4u o; o.x = pk2(q[0 * 65], q[1 * 65]); o.y = pk2(q[2 * 65], q[3 * 65]); o.z = pk2(q[4 * 65], q[5 * 65]); o.w = pk2(q[6 * 65], q[7 * 65]);
;         *(v4u*)(WT + (size_t)(nd0 + n) * ldwt + koff + k0 + 8 * c) = o; }
;     asm volatile("s_waitcnt lgkmcnt(0)" ::: "memory");
	v_lshl_add_u64 v[96:97], v[78:79], 0, v[64:65]
	v_lshl_add_u64 v[98:99], v[78:79], 0, v[66:67]
	v_lshl_add_u64 v[100:101], v[78:79], 0, v[68:69]
	v_lshl_add_u64 v[102:103], v[78:79], 0, v[70:71]
	v_lshl_add_u64 v[104:105], v[78:79], 0, v[72:73]
	v_lshl_add_u64 v[106:107], v[78:79], 0, v[74:75]
	v_lshl_add_u64 v[108:109], v[78:79], 0, v[76:77]
	global_load_dwordx4 v[46:49], v[46:47], off
	s_nop 0
	global_load_dwordx4 v[50:53], v[80:81], off
	global_load_dwordx4 v[54:57], v[82:83], off
	global_load_dwordx4 v[58:61], v[84:85], off
	global_load_dwordx4 v[62:65], v[86:87], off
	global_load_dwordx4 v[66:69], v[88:89], off
	global_load_dwordx4 v[70:73], v[90:91], off
	global_load_dwordx4 v[74:77], v[92:93], off
	global_load_dwordx4 v[78:81], v[94:95], off
	global_load_dwordx4 v[82:85], v[96:97], off
	s_nop 0
	global_load_dwordx4 v[86:89], v[98:99], off
	global_load_dwordx4 v[90:93], v[100:101], off
	global_load_dwordx4 v[94:97], v[102:103], off
	s_nop 0
	global_load_dwordx4 v[98:101], v[104:105], off
	s_nop 0
	global_load_dwordx4 v[102:105], v[106:107], off
	s_nop 0
	global_load_dwordx4 v[106:109], v[108:109], off
	v_add_u32_e32 v6, s0, v9
	s_ashr_i32 s3, s2, 31
	v_ashrrev_i32_e32 v7, 31, v6
	v_lshl_add_u64 v[4:5], s[2:3], 1, v[0:1]
	v_lshlrev_b64 v[122:123], 13, v[6:7]
	v_add_u32_e32 v110, 8, v6
	v_lshl_add_u64 v[122:123], v[4:5], 0, v[122:123]
	v_ashrrev_i32_e32 v111, 31, v110
	v_lshlrev_b64 v[110:111], 13, v[110:111]
	v_add_u32_e32 v112, 16, v6
	v_lshl_add_u64 v[110:111], v[4:5], 0, v[110:111]
	v_ashrrev_i32_e32 v113, 31, v112
	v_lshlrev_b64 v[112:113], 13, v[112:113]
	v_add_u32_e32 v114, 24, v6
	v_lshl_add_u64 v[112:113], v[4:5], 0, v[112:113]
	s_waitcnt vmcnt(15)
	ds_write2_b32 v11, v46, v47 offset1:1
	ds_write2_b32 v11, v48, v49 offset0:2 offset1:3
	s_waitcnt vmcnt(14)
	ds_write2_b32 v12, v50, v51 offset1:1
	ds_write2_b32 v13, v52, v53 offset1:1
	s_waitcnt vmcnt(13)
	ds_write2_b32 v14, v54, v55 offset1:1
	ds_write2_b32 v15, v56, v57 offset1:1
	s_waitcnt vmcnt(12)
	ds_write2_b32 v16, v58, v59 offset1:1
	ds_write2_b32 v17, v60, v61 offset1:1
	s_waitcnt vmcnt(11)
	ds_write2_b32 v18, v62, v63 offset1:1
	ds_write2_b32 v19, v64, v65 offset1:1
	s_waitcnt vmcnt(10)
	ds_write2_b32 v20, v66, v67 offset1:1
	ds_write2_b32 v21, v68, v69 offset1:1
	s_waitcnt vmcnt(9)
	ds_write2_b32 v22, v70, v71 offset1:1
	ds_write2_b32 v23, v72, v73 offset1:1
	s_waitcnt vmcnt(8)
	ds_write2_b32 v24, v74, v75 offset1:1
	ds_write2_b32 v25, v76, v77 offset1:1
	s_waitcnt vmcnt(7)
	ds_write2_b32 v26, v78, v79 offset1:1
	ds_write2_b32 v27, v80, v81 offset1:1
	s_waitcnt vmcnt(6)
	ds_write2_b32 v28, v82, v83 offset1:1
	ds_write2_b32 v29, v84, v85 offset1:1
	s_waitcnt vmcnt(5)
	ds_write2_b32 v30, v86, v87 offset1:1
	ds_write2_b32 v31, v88, v89 offset1:1
	s_waitcnt vmcnt(4)
	ds_write2_b32 v32, v90, v91 offset1:1
	ds_write2_b32 v33, v92, v93 offset1:1
	s_waitcnt vmcnt(3)
	ds_write2_b32 v34, v94, v95 offset1:1
	ds_write2_b32 v35, v96, v97 offset1:1
	s_waitcnt vmcnt(2)
	ds_write2_b32 v36, v98, v99 offset1:1
	ds_write2_b32 v37, v100, v101 offset1:1
	s_waitcnt vmcnt(1)
	ds_write2_b32 v38, v102, v103 offset1:1
	ds_write2_b32 v39, v104, v105 offset1:1
	s_waitcnt vmcnt(0)
	ds_write2_b32 v42, v106, v107 offset1:1
	ds_write2_b32 v43, v108, v109 offset1:1
	s_waitcnt lgkmcnt(0)
	ds_read2_b32 v[46:47], v10 offset1:65
	s_waitcnt lgkmcnt(0)
	v_cvt_pk_bf16_f32 v46, v46, v47
	ds_read2_b32 v[48:49], v10 offset0:130 offset1:195
	s_waitcnt lgkmcnt(0)
	v_cvt_pk_bf16_f32 v47, v48, v49
	ds_read2_b32 v[48:49], v44 offset0:4 offset1:69
	s_waitcnt lgkmcnt(0)
	v_cvt_pk_bf16_f32 v48, v48, v49
	ds_read2_b32 v[50:51], v44 offset0:134 offset1:199
	s_waitcnt lgkmcnt(0)
	v_cvt_pk_bf16_f32 v49, v50, v51
	ds_read2_b32 v[50:51], v10 offset0:8 offset1:73
	global_store_dwordx4 v[122:123], v[46:49], off
	v_ashrrev_i32_e32 v115, 31, v114
	v_lshlrev_b64 v[114:115], 13, v[114:115]
	s_waitcnt lgkmcnt(0)
	v_cvt_pk_bf16_f32 v46, v50, v51
	ds_read2_b32 v[48:49], v10 offset0:138 offset1:203
	s_waitcnt lgkmcnt(0)
	v_cvt_pk_bf16_f32 v47, v48, v49
	ds_read2_b32 v[48:49], v44 offset0:12 offset1:77
	s_waitcnt lgkmcnt(0)
	v_cvt_pk_bf16_f32 v48, v48, v49
	ds_read2_b32 v[50:51], v44 offset0:142 offset1:207
	s_waitcnt lgkmcnt(0)
	v_cvt_pk_bf16_f32 v49, v50, v51
	ds_read2_b32 v[50:51], v10 offset0:16 offset1:81
	global_store_dwordx4 v[110:111], v[46:49], off
	v_add_u32_e32 v116, 32, v6
	v_lshl_add_u64 v[114:115], v[4:5], 0, v[114:115]
	s_waitcnt lgkmcnt(0)
; #define LAS __attribute__((address_space(3)))
; __device__ __forceinline__ unsigned pk2(float lo, float hi) { return pg8::cvt_pk_bf16(lo, hi); }
; template <bool GATEMAP = false>
; __device__ __forceinline__ void p0_transpose_item(const float* W, int N, bf16* WT, int ldwt, int koff, const float* gain, LAS float* scr, int item, int lane) {
;     ...
;     for (int j = 0; j < 8; ++j) { const int n = (lane >> 3) + 8 * j; const LAS float* q = scr + (8 * c) * 65 + n;
;         v4u o; o.x = pk2(q[0 * 65], q[1 * 65]); o.y = pk2(q[2 * 65], q[3 * 65]); o.z = pk2(q[4 * 65], q[5 * 65]); o.w = pk2(q[6 * 65], q[7 * 65]);
;         *(v4u*)(WT + (size_t)(nd0 + n) * ldwt + koff + k0 + 8 * c) = o; }
;     asm volatile("s_waitcnt lgkmcnt(0)" ::: "memory");
; template <int PART>
; __device__ __forceinline__ void phase_prologue_late(const Params& p, LAS unsigned char* lds, int cu0) {
;     ...
;     for (int it = gw; it < I_W2; it += NGW) p0_transpose_item(p.in[23], D, (bf16*)(ws + WS_W2_0), FF, 0, nullptr, scr, it, lane);
;     {
;         const float* Wp = p.in[15]; const float* sc = p.in[16]; const float* Wo = p.in[21]; bf16* WT = (bf16*)(ws + WS_WOUT1);
;         for (int it = gw; it < 1024; it += NGW) {
;             const int g = it >> 8, cb = (it >> 4) & 15, nb2 = it & 15, n = nb2 * 64 + lane;
;             float acc[8];
; #pragma unroll
;             for (int i = 0; i < 8; ++i) acc[i] = 0.f;
;             const float* wp = Wp + ((size_t)g * 128 + cb * 8) * 128;
	v_cvt_pk_bf16_f32 v46, v50, v51
	ds_read2_b32 v[48:49], v10 offset0:146 offset1:211
	s_waitcnt lgkmcnt(0)
	v_cvt_pk_bf16_f32 v47, v48, v49
	ds_read2_b32 v[48:49], v44 offset0:20 offset1:85
	s_waitcnt lgkmcnt(0)
	v_cvt_pk_bf16_f32 v48, v48, v49
	ds_read2_b32 v[50:51], v44 offset0:150 offset1:215
	s_waitcnt lgkmcnt(0)
	v_cvt_pk_bf16_f32 v49, v50, v51
	ds_read2_b32 v[50:51], v10 offset0:24 offset1:89
	global_store_dwordx4 v[112:113], v[46:49], off
	v_ashrrev_i32_e32 v117, 31, v116
	v_lshlrev_b64 v[116:117], 13, v[116:117]
	s_waitcnt lgkmcnt(0)
	v_cvt_pk_bf16_f32 v46, v50, v51
	ds_read2_b32 v[48:49], v10 offset0:154 offset1:219
	s_waitcnt lgkmcnt(0)
	v_cvt_pk_bf16_f32 v47, v48, v49
	ds_read2_b32 v[48:49], v44 offset0:28 offset1:93
	s_waitcnt lgkmcnt(0)
	v_cvt_pk_bf16_f32 v48, v48, v49
	ds_read2_b32 v[50:51], v44 offset0:158 offset1:223
	s_waitcnt lgkmcnt(0)
	v_cvt_pk_bf16_f32 v49, v50, v51
	ds_read2_b32 v[50:51], v10 offset0:32 offset1:97
	global_store_dwordx4 v[114:115], v[46:49], off
	v_add_u32_e32 v118, 40, v6
	v_lshl_add_u64 v[116:117], v[4:5], 0, v[116:117]
	s_waitcnt lgkmcnt(0)
	v_cvt_pk_bf16_f32 v46, v50, v51
	ds_read2_b32 v[48:49], v10 offset0:162 offset1:227
	s_waitcnt lgkmcnt(0)
	v_cvt_pk_bf16_f32 v47, v48, v49
	ds_read2_b32 v[48:49], v44 offset0:36 offset1:101
	s_waitcnt lgkmcnt(0)
	v_cvt_pk_bf16_f32 v48, v48, v49
	ds_read2_b32 v[50:51], v44 offset0:166 offset1:231
	s_waitcnt lgkmcnt(0)
	v_cvt_pk_bf16_f32 v49, v50, v51
	v_ashrrev_i32_e32 v119, 31, v118
	ds_read2_b32 v[50:51], v10 offset0:40 offset1:105
	global_store_dwordx4 v[116:117], v[46:49], off
	v_lshlrev_b64 v[118:119], 13, v[118:119]
	v_add_u32_e32 v120, 48, v6
	s_waitcnt lgkmcnt(0)
	v_cvt_pk_bf16_f32 v46, v50, v51
	ds_read2_b32 v[48:49], v10 offset0:170 offset1:235
	s_waitcnt lgkmcnt(0)
	v_cvt_pk_bf16_f32 v47, v48, v49
	ds_read2_b32 v[48:49], v44 offset0:44 offset1:109
	v_lshl_add_u64 v[118:119], v[4:5], 0, v[118:119]
	s_waitcnt lgkmcnt(0)
	v_cvt_pk_bf16_f32 v48, v48, v49
	ds_read2_b32 v[50:51], v44 offset0:174 offset1:239
	s_waitcnt lgkmcnt(0)
	v_cvt_pk_bf16_f32 v49, v50, v51
	v_ashrrev_i32_e32 v121, 31, v120
	ds_read2_b32 v[50:51], v10 offset0:48 offset1:113
	global_store_dwordx4 v[118:119], v[46:49], off
	v_lshlrev_b64 v[120:121], 13, v[120:121]
	v_add_u32_e32 v6, 56, v6
	s_waitcnt lgkmcnt(0)
	v_cvt_pk_bf16_f32 v46, v50, v51
	ds_read2_b32 v[48:49], v10 offset0:178 offset1:243
	s_waitcnt lgkmcnt(0)
	v_cvt_pk_bf16_f32 v47, v48, v49
	ds_read2_b32 v[48:49], v44 offset0:52 offset1:117
	v_lshl_add_u64 v[120:121], v[4:5], 0, v[120:121]
	s_waitcnt lgkmcnt(0)
	v_cvt_pk_bf16_f32 v48, v48, v49
	ds_read2_b32 v[50:51], v44 offset0:182 offset1:247
	s_waitcnt lgkmcnt(0)
	v_cvt_pk_bf16_f32 v49, v50, v51
	v_ashrrev_i32_e32 v7, 31, v6
	ds_read2_b32 v[50:51], v10 offset0:56 offset1:121
	global_store_dwordx4 v[120:121], v[46:49], off
	v_lshlrev_b64 v[6:7], 13, v[6:7]
	v_lshl_add_u64 v[4:5], v[4:5], 0, v[6:7]
	s_waitcnt lgkmcnt(0)
	v_cvt_pk_bf16_f32 v46, v50, v51
	ds_read2_b32 v[48:49], v10 offset0:186 offset1:251
	s_waitcnt lgkmcnt(0)
	v_cvt_pk_bf16_f32 v47, v48, v49
	ds_read2_b32 v[48:49], v44 offset0:60 offset1:125
	s_waitcnt lgkmcnt(0)
	v_cvt_pk_bf16_f32 v48, v48, v49
	ds_read2_b32 v[50:51], v44 offset0:190 offset1:255
	s_waitcnt lgkmcnt(0)
	v_cvt_pk_bf16_f32 v49, v50, v51
	global_store_dwordx4 v[4:5], v[46:49], off
	s_waitcnt lgkmcnt(0)
	s_add_i32 s13, s13, s12
	s_add_i32 s4, s4, s5
	s_cmpk_gt_i32 s13, 0x3ff
	s_cbranch_scc0 .LBB0_508
	s_cmpk_lg_i32 s7, 0xc0
	s_cbranch_scc1 .Lprep2_skipw2
	s_branch .LBB0_513
.Lprep2_skipw2:
	s_add_u32 s0, s72, 0x1b00000
	v_readlane_b32 s52, v254, 5
	s_addc_u32 s1, s73, 0
	v_readlane_b32 s62, v254, 15
	v_readlane_b32 s63, v254, 16
	s_add_u32 s13, s62, 0xf000
	s_addc_u32 s14, s63, 0
	s_lshl_b32 s2, s10, 9
	s_lshl_b32 s3, s6, 9
	s_lshl_b32 s15, s9, 6
	s_sub_i32 s16, s2, s3
	v_mov_b32_e32 v25, 0
	s_mov_b64 s[2:3], 0x10000
	s_mov_b32 s5, 0
	v_readlane_b32 s53, v254, 6
	v_readlane_b32 s54, v254, 7
	v_readlane_b32 s55, v254, 8
	v_readlane_b32 s56, v254, 9
	v_readlane_b32 s57, v254, 10
	v_readlane_b32 s58, v254, 11
	v_readlane_b32 s59, v254, 12
	v_readlane_b32 s60, v254, 13
	v_readlane_b32 s61, v254, 14
	v_readlane_b32 s64, v254, 17
	v_readlane_b32 s65, v254, 18
	v_readlane_b32 s66, v254, 19
	v_readlane_b32 s67, v254, 20
